# speedup vs baseline: 1.0161x; 1.0161x over previous
; DI unsigned pk2(float lo, float hi) { unsigned r; asm("v_cvt_pk_bf16_f32 %0, %1, %2" : "=v"(r) : "v"(lo), "v"(hi)); return r; }
; DI void unpack8(const u32x4 u, float* f) { f[0] = bflo(u.x); f[1] = bfhi(u.x); f[2] = bflo(u.y); f[3] = bfhi(u.y); f[4] = bflo(u.z); f[5] = bfhi(u.z); f[6] = bflo(u.w); f[7] = bfhi(u.w); }
; DI void mix_gmlp(CP& p, int l, int ci, LAS unsigned char* lds) {
;     ...
;     if (j < nvalid) {
;       const u32x4 raw = *(const u32x4*)(proj + (size_t)(r0 + j) * NPROJ + C_AV + 8 * lane);
;       float f[8]; unpack8(raw, f);
;       float s = 0.f;
; #pragma unroll
;       for (int e = 0; e < 8; ++e) s += f[e];
;       const float mean = wave_sum(s, lane) * (1.f / 512.f);
;       float s2 = 0.f;
; #pragma unroll
;       for (int e = 0; e < 8; ++e) { f[e] -= mean; s2 += f[e] * f[e]; }
;       const float rstd = rsqrtf(wave_sum(s2, lane) * (1.f / 512.f) + EPS);
; #pragma unroll
;       for (int e = 0; e < 8; ++e) f[e] = f[e] * rstd * g8[e] + b8[e];
;       dst[0] = pk2(f[0], f[1]); dst[1] = pk2(f[2], f[3]); dst[2] = pk2(f[4], f[5]); dst[3] = pk2(f[6], f[7]);
.LBB0_156:
	s_andn2_saveexec_b64 s[16:17], s[8:9]
	s_cbranch_execz .LBB0_153
	global_load_dwordx4 v[16:19], v[28:29], off
	s_andn2_b64 vcc, exec, s[10:11]
	s_waitcnt vmcnt(0)
	v_lshlrev_b32_e32 v22, 16, v16
	v_and_b32_e32 v23, 0xffff0000, v16
	v_add_f32_e32 v35, 0, v22
	v_lshlrev_b32_e32 v16, 16, v17
	v_add_f32_e32 v35, v35, v23
	v_and_b32_e32 v17, 0xffff0000, v17
	v_add_f32_e32 v35, v35, v16
	v_lshlrev_b32_e32 v20, 16, v18
	v_add_f32_e32 v35, v35, v17
	v_and_b32_e32 v21, 0xffff0000, v18
	v_add_f32_e32 v35, v35, v20
	v_lshlrev_b32_e32 v18, 16, v19
	v_add_f32_e32 v35, v35, v21
	v_and_b32_e32 v19, 0xffff0000, v19
	v_add_f32_e32 v35, v35, v18
	v_add_f32_e32 v35, v35, v19
	s_nop 1
	v_add_f32_dpp v35, v35, v35 quad_perm:[1,0,3,2] row_mask:0xf bank_mask:0xf
	s_nop 1
	v_add_f32_dpp v35, v35, v35 quad_perm:[2,3,0,1] row_mask:0xf bank_mask:0xf
	s_nop 1
	v_add_f32_dpp v35, v35, v35 row_half_mirror row_mask:0xf bank_mask:0xf
	s_nop 1
	v_add_f32_dpp v35, v35, v35 row_mirror row_mask:0xf bank_mask:0xf
	v_mov_b32_e32 v36, v35
	s_nop 1
	v_permlane16_swap_b32_e32 v35, v36
	s_nop 1
	v_add_f32_e32 v35, v35, v36
	v_mov_b32_e32 v36, v35
	s_nop 1
	v_permlane32_swap_b32_e32 v35, v36
	s_nop 1
	v_add_f32_e32 v35, v35, v36
	v_mul_f32_e32 v36, 0x3b000000, v35
	v_pk_add_f32 v[22:23], v[22:23], v[36:37] op_sel_hi:[1,0] neg_lo:[0,1] neg_hi:[0,1]
	v_pk_add_f32 v[16:17], v[16:17], v[36:37] op_sel_hi:[1,0] neg_lo:[0,1] neg_hi:[0,1]
	v_pk_add_f32 v[20:21], v[20:21], v[36:37] op_sel_hi:[1,0] neg_lo:[0,1] neg_hi:[0,1]
	v_pk_add_f32 v[18:19], v[18:19], v[36:37] op_sel_hi:[1,0] neg_lo:[0,1] neg_hi:[0,1]
	v_pk_mul_f32 v[36:37], v[22:23], v[22:23]
	v_pk_mul_f32 v[38:39], v[16:17], v[16:17]
	v_add_f32_e32 v35, v36, v37
	v_add_f32_e32 v35, v38, v35
	v_pk_mul_f32 v[40:41], v[20:21], v[20:21]
	v_add_f32_e32 v35, v39, v35
	v_add_f32_e32 v35, v40, v35
	v_pk_mul_f32 v[42:43], v[18:19], v[18:19]
	v_add_f32_e32 v35, v41, v35
	v_add_f32_e32 v35, v42, v35
	v_add_f32_e32 v35, v43, v35
	s_nop 1
	v_add_f32_dpp v35, v35, v35 quad_perm:[1,0,3,2] row_mask:0xf bank_mask:0xf
	s_nop 1
	v_add_f32_dpp v35, v35, v35 quad_perm:[2,3,0,1] row_mask:0xf bank_mask:0xf
	s_nop 1
	v_add_f32_dpp v35, v35, v35 row_half_mirror row_mask:0xf bank_mask:0xf
	s_nop 1
	v_add_f32_dpp v35, v35, v35 row_mirror row_mask:0xf bank_mask:0xf
	v_mov_b32_e32 v36, v35
	s_nop 1
	v_permlane16_swap_b32_e32 v35, v36
	s_nop 1
	v_add_f32_e32 v35, v35, v36
	v_mov_b32_e32 v36, v35
	s_nop 1
	v_permlane32_swap_b32_e32 v35, v36
	s_nop 1
	v_add_f32_e32 v35, v35, v36
	v_fmamk_f32 v35, v35, 0x3b000000, v234
	v_mul_f32_e32 v36, 0x4b800000, v35
	v_cmp_gt_f32_e64 s[8:9], s81, v35
	s_nop 1
	v_cndmask_b32_e64 v35, v35, v36, s[8:9]
	v_rsq_f32_e32 v35, v35
	s_nop 0
	v_mul_f32_e32 v36, 0x45800000, v35
	v_cndmask_b32_e64 v36, v35, v36, s[8:9]
	v_pk_mul_f32 v[22:23], v[22:23], v[36:37] op_sel_hi:[1,0]
	v_pk_mul_f32 v[16:17], v[16:17], v[36:37] op_sel_hi:[1,0]
	v_pk_mul_f32 v[38:39], v[20:21], v[36:37] op_sel_hi:[1,0]
	v_pk_mul_f32 v[18:19], v[18:19], v[36:37] op_sel_hi:[1,0]
	v_pk_fma_f32 v[20:21], v[0:1], v[22:23], v[8:9]
	v_pk_fma_f32 v[22:23], v[2:3], v[16:17], v[10:11]
	v_pk_fma_f32 v[16:17], v[4:5], v[38:39], v[12:13]
	v_pk_fma_f32 v[18:19], v[6:7], v[18:19], v[14:15]
	v_cvt_pk_bf16_f32 v35, v20, v21
	v_cvt_pk_bf16_f32 v36, v22, v23
	v_cvt_pk_bf16_f32 v37, v16, v17
	s_nop 0
	v_cvt_pk_bf16_f32 v38, v18, v19
	ds_write2_b32 v27, v35, v36 offset1:1
	ds_write2_b32 v27, v37, v38 offset0:2 offset1:3
	s_cbranch_vccnz .LBB0_153
	v_lshl_add_u64 v[36:37], v[30:31], 0, s[12:13]
	v_add_co_u32_e32 v36, vcc, 0x1050e000, v36
	s_nop 1
	v_addc_co_u32_e32 v37, vcc, 0, v37, vcc
	global_store_dwordx4 v[36:37], v[20:23], off
	global_store_dwordx4 v[36:37], v[16:19], off offset:16
	s_branch .LBB0_153
